# v56 + G1/G4 full-line mainloop software-pipelined across the barrier
# baseline (speedup 1.0000x reference)
.LBB1_54:
	v_readlane_b32 s4, v242, 0
	s_lshl_b32 s5, s2, 3
	s_and_b32 s6, s4, 7
	s_or_b32 s5, s6, s5
	s_mul_i32 s5, s5, s55
	s_ashr_i32 s4, s4, 3
	s_add_i32 s4, s5, s4
	s_cmpk_lt_i32 s4, 0x400
	s_mov_b64 s[40:41], -1
	s_cbranch_scc0 .LBB1_53
	s_ashr_i32 s5, s4, 31
	s_lshr_b32 s5, s5, 25
	s_add_i32 s5, s4, s5
	s_and_b32 s6, s5, 0xffffff80
	s_sub_i32 s7, s4, s6
	s_ashr_i32 s4, s7, 31
	s_lshr_b32 s4, s4, 29
	s_add_i32 s6, s7, s4
	s_and_b32 s4, s6, 0xfffff8
	s_sub_i32 s4, s7, s4
	s_lshl_b32 s5, s5, 4
	s_and_b32 s5, s5, 0xfffff800
	s_lshl_b32 s4, s4, 8
	s_add_i32 s4, s4, s5
	s_lshl_b32 s5, s6, 4
	v_mov_b32_e32 v134, v162
	s_and_b32 s40, s5, 0xffffff80
	s_movk_i32 s10, 0x78
	v_readfirstlane_b32 s5, v134
	v_lshrrev_b32_e32 v0, 3, v134
	v_and_b32_e32 v0, 6, v0
	s_and_b32 s8, s5, 0xffffffc0
	s_waitcnt lgkmcnt(0)
	v_bfe_u32 v2, v134, 2, 4
	v_lshrrev_b32_e64 v0, v0, s10
	s_add_i32 s8, s8, s4
	v_xor_b32_e32 v3, v0, v134
	v_or_b32_e32 v0, s8, v2
	v_ashrrev_i32_e32 v1, 31, v0
	v_lshlrev_b64 v[0:1], 11, v[0:1]
	v_lshlrev_b32_e32 v3, 4, v3
	v_lshl_add_u64 v[0:1], s[74:75], 0, v[0:1]
	v_and_b32_e32 v128, 48, v3
	s_load_dwordx16 s[80:95], s[0:1], 0xc0
	s_ashr_i32 s6, s5, 6
	v_lshl_add_u64 v[130:131], v[0:1], 0, v[128:129]
	v_or_b32_e32 v0, s40, v2
	v_lshl_add_u32 v0, s6, 5, v0
	v_ashrrev_i32_e32 v1, 31, v0
	v_lshlrev_b64 v[0:1], 11, v[0:1]
	s_waitcnt lgkmcnt(0)
	v_lshl_add_u64 v[0:1], s[92:93], 0, v[0:1]
	v_lshl_add_u64 v[132:133], v[0:1], 0, v[128:129]
	v_lshrrev_b32_e32 v0, 1, v134
	v_and_b32_e32 v0, 6, v0
	v_bfe_u32 v136, v134, 4, 2
	s_lshl_b32 s8, s6, 12
	v_lshrrev_b32_e64 v0, v0, s10
	v_and_b32_e32 v135, 15, v134
	s_lshl_b32 s9, s6, 11
	s_and_b32 s6, s5, 0xffffff80
	v_bitop3_b32 v0, v0, v136, 3 bitop3:0x6c
	s_and_b32 s5, s5, 64
	s_add_i32 s10, s8, 16
	v_lshlrev_b32_e32 v138, 4, v0
	v_or_b32_e32 v0, s5, v135
	s_mov_b32 m0, s10
	v_lshlrev_b32_e32 v139, 6, v0
	s_barrier
	v_lshl_add_u64 v[0:1], v[130:131], 0, s[34:35]
	s_add_i32 m0, s10, 0x400
	s_mov_b64 s[12:13], 0x10000
	v_lshl_add_u64 v[0:1], v[130:131], 0, s[12:13]
	s_add_i32 m0, s10, 0x800
	s_mov_b64 s[12:13], 0x18000
	v_lshl_add_u64 v[0:1], v[130:131], 0, s[12:13]
	s_add_i32 m0, s10, 0xc00
	s_sub_i32 s11, s10, s9
	s_add_i32 m0, s11, 0x4000
	v_lshl_add_u64 v[0:1], v[132:133], 0, s[34:35]
	s_add_i32 m0, s11, 0x4400
	s_mov_b64 s[12:13], 0x8040
	v_lshl_add_u64 v[0:1], v[130:131], 0, 64
	s_add_i32 m0, s10, 0x6000
	s_mov_b64 s[14:15], 0x10040
	v_lshl_add_u64 v[0:1], v[130:131], 0, s[12:13]
	s_add_i32 m0, s10, 0x6400
	v_or_b32_e32 v128, s6, v135
	v_lshl_add_u64 v[0:1], v[130:131], 0, s[14:15]
	s_add_i32 m0, s10, 0x6800
	s_mov_b64 s[14:15], 0x18040
	v_lshl_add_u64 v[0:1], v[130:131], 0, s[14:15]
	s_add_i32 m0, s10, 0x6c00
	v_lshlrev_b32_e32 v137, 6, v128
	v_lshl_add_u64 v[0:1], v[132:133], 0, 64
	s_add_i32 m0, s11, 0xa000
	s_mov_b32 s10, 0
	v_lshl_add_u64 v[0:1], v[132:133], 0, s[12:13]
	s_add_i32 m0, s11, 0xa400
	s_mov_b32 s11, 0
	v_mov_b32_e32 v0, 0
	v_mov_b32_e32 v1, v0
	v_mov_b32_e32 v2, v0
	v_mov_b32_e32 v3, v0
	v_mov_b32_e32 v4, v0
	v_mov_b32_e32 v5, v0
	v_mov_b32_e32 v6, v0
	v_mov_b32_e32 v7, v0
	v_mov_b32_e32 v8, v0
	v_mov_b32_e32 v9, v0
	v_mov_b32_e32 v10, v0
	v_mov_b32_e32 v11, v0
	v_mov_b32_e32 v12, v0
	v_mov_b32_e32 v13, v0
	v_mov_b32_e32 v14, v0
	v_mov_b32_e32 v15, v0
	v_mov_b32_e32 v16, v0
	v_mov_b32_e32 v17, v0
	v_mov_b32_e32 v18, v0
	v_mov_b32_e32 v19, v0
	v_mov_b32_e32 v20, v0
	v_mov_b32_e32 v21, v0
	v_mov_b32_e32 v22, v0
	v_mov_b32_e32 v23, v0
	v_mov_b32_e32 v24, v0
	v_mov_b32_e32 v25, v0
	v_mov_b32_e32 v26, v0
	v_mov_b32_e32 v27, v0
	v_mov_b32_e32 v28, v0
	v_mov_b32_e32 v29, v0
	v_mov_b32_e32 v30, v0
	v_mov_b32_e32 v31, v0
	v_mov_b32_e32 v32, v0
	v_mov_b32_e32 v33, v0
	v_mov_b32_e32 v34, v0
	v_mov_b32_e32 v35, v0
	v_mov_b32_e32 v36, v0
	v_mov_b32_e32 v37, v0
	v_mov_b32_e32 v38, v0
	v_mov_b32_e32 v39, v0
	v_mov_b32_e32 v40, v0
	v_mov_b32_e32 v41, v0
	v_mov_b32_e32 v42, v0
	v_mov_b32_e32 v43, v0
	v_mov_b32_e32 v44, v0
	v_mov_b32_e32 v45, v0
	v_mov_b32_e32 v46, v0
	v_mov_b32_e32 v47, v0
	v_mov_b32_e32 v48, v0
	v_mov_b32_e32 v49, v0
	v_mov_b32_e32 v50, v0
	v_mov_b32_e32 v51, v0
	v_mov_b32_e32 v52, v0
	v_mov_b32_e32 v53, v0
	v_mov_b32_e32 v54, v0
	v_mov_b32_e32 v55, v0
	v_mov_b32_e32 v56, v0
	v_mov_b32_e32 v57, v0
	v_mov_b32_e32 v58, v0
	v_mov_b32_e32 v59, v0
	v_mov_b32_e32 v60, v0
	v_mov_b32_e32 v61, v0
	v_mov_b32_e32 v62, v0
	v_mov_b32_e32 v63, v0
	v_mov_b32_e32 v64, v0
	v_mov_b32_e32 v65, v0
	v_mov_b32_e32 v66, v0
	v_mov_b32_e32 v67, v0
	v_mov_b32_e32 v68, v0
	v_mov_b32_e32 v69, v0
	v_mov_b32_e32 v70, v0
	v_mov_b32_e32 v71, v0
	v_mov_b32_e32 v72, v0
	v_mov_b32_e32 v73, v0
	v_mov_b32_e32 v74, v0
	v_mov_b32_e32 v75, v0
	v_mov_b32_e32 v84, v0
	v_mov_b32_e32 v85, v0
	v_mov_b32_e32 v86, v0
	v_mov_b32_e32 v87, v0
	v_mov_b32_e32 v96, v0
	v_mov_b32_e32 v97, v0
	v_mov_b32_e32 v98, v0
	v_mov_b32_e32 v99, v0
	v_mov_b32_e32 v100, v0
	v_mov_b32_e32 v101, v0
	v_mov_b32_e32 v102, v0
	v_mov_b32_e32 v103, v0
	v_mov_b32_e32 v104, v0
	v_mov_b32_e32 v105, v0
	v_mov_b32_e32 v106, v0
	v_mov_b32_e32 v107, v0
	v_mov_b32_e32 v108, v0
	v_mov_b32_e32 v109, v0
	v_mov_b32_e32 v110, v0
	v_mov_b32_e32 v111, v0
	v_mov_b32_e32 v112, v0
	v_mov_b32_e32 v113, v0
	v_mov_b32_e32 v114, v0
	v_mov_b32_e32 v115, v0
	v_mov_b32_e32 v116, v0
	v_mov_b32_e32 v117, v0
	v_mov_b32_e32 v118, v0
	v_mov_b32_e32 v119, v0
	v_mov_b32_e32 v120, v0
	v_mov_b32_e32 v121, v0
	v_mov_b32_e32 v122, v0
	v_mov_b32_e32 v123, v0
	v_mov_b32_e32 v124, v0
	v_mov_b32_e32 v125, v0
	v_mov_b32_e32 v126, v0
	v_mov_b32_e32 v127, v0
	v_mov_b32_e32 v76, v0
	v_mov_b32_e32 v77, v0
	v_mov_b32_e32 v78, v0
	v_mov_b32_e32 v79, v0
	v_mov_b32_e32 v80, v0
	v_mov_b32_e32 v81, v0
	v_mov_b32_e32 v82, v0
	v_mov_b32_e32 v83, v0
	v_mov_b32_e32 v88, v0
	v_mov_b32_e32 v89, v0
	v_mov_b32_e32 v90, v0
	v_mov_b32_e32 v91, v0
	v_mov_b32_e32 v92, v0
	v_mov_b32_e32 v93, v0
	v_mov_b32_e32 v94, v0
	v_mov_b32_e32 v95, v0
	s_mov_b64 s[16:17], 0x10080
	v_and_b32_e32 v204, 15, v168
	v_lshrrev_b32_e32 v205, 4, v168
	v_bfe_u32 v206, v168, 1, 3
	v_xor_b32_e32 v205, v205, v206
	v_lshlrev_b32_e32 v205, 4, v205
	v_readfirstlane_b32 s15, v162
	v_readfirstlane_b32 s18, v130
	v_readfirstlane_b32 s19, v131
	v_readfirstlane_b32 s28, v132
	v_readfirstlane_b32 s29, v133
	s_lshr_b32 s15, s15, 6
	s_lshl_b32 s54, s15, 12
	s_lshr_b32 s41, s15, 1
	s_and_b32 s42, s15, 1
	v_lshl_add_u32 v206, s41, 6, v204
	v_lshl_add_u32 v196, v206, 7, v205
	v_xor_b32_e32 v197, 64, v196
	v_lshl_add_u32 v206, s42, 6, v204
	v_lshl_add_u32 v198, v206, 7, v205
	v_xor_b32_e32 v199, 64, v198
	v_add_u32_e32 v198, 0xc010, v198
	v_add_u32_e32 v199, 0xc010, v199
	v_lshrrev_b32_e32 v206, 3, v168
	v_and_b32_e32 v207, 7, v168
	v_lshrrev_b32_e32 v204, 1, v206
	v_xor_b32_e32 v207, v207, v204
	v_lshlrev_b32_e32 v207, 4, v207
	v_lshl_add_u32 v200, v206, 11, v207
	v_xor_b32_e32 v201, 64, v200
	s_lshl_b32 s42, s42, 16
	s_sub_u32 s18, s18, s42
	s_subb_u32 s19, s19, 0
	s_add_i32 s41, s54, 16
	s_add_i32 m0, s41, 0x0
	s_nop 0
	global_load_lds_dwordx4 v200, s[18:19]
	s_add_i32 m0, s41, 0x400
	s_add_u32 s52, s18, 0x4000
	s_addc_u32 s53, s19, 0
	global_load_lds_dwordx4 v201, s[52:53]
	s_add_i32 m0, s41, 0x800
	s_add_u32 s52, s18, 0x8000
	s_addc_u32 s53, s19, 0
	global_load_lds_dwordx4 v200, s[52:53]
	s_add_i32 m0, s41, 0xc00
	s_add_u32 s52, s18, 0xc000
	s_addc_u32 s53, s19, 0
	global_load_lds_dwordx4 v201, s[52:53]
	s_add_i32 m0, s54, 0xc010
	s_nop 0
	global_load_lds_dwordx4 v200, s[28:29]
	s_add_i32 m0, s54, 0xc410
	s_add_u32 s52, s28, 0x4000
	s_addc_u32 s53, s29, 0
	global_load_lds_dwordx4 v201, s[52:53]
	s_add_i32 m0, s54, 0xc810
	s_add_u32 s52, s28, 0x8000
	s_addc_u32 s53, s29, 0
	global_load_lds_dwordx4 v200, s[52:53]
	s_add_i32 m0, s54, 0xcc10
	s_add_u32 s52, s28, 0xc000
	s_addc_u32 s53, s29, 0
	global_load_lds_dwordx4 v201, s[52:53]
	s_add_u32 s50, s18, 0x20000
	s_addc_u32 s51, s19, 0
	s_add_i32 m0, s41, 0x4000
	s_nop 0
	global_load_lds_dwordx4 v200, s[50:51]
	s_add_i32 m0, s41, 0x4400
	s_add_u32 s52, s50, 0x4000
	s_addc_u32 s53, s51, 0
	global_load_lds_dwordx4 v201, s[52:53]
	s_add_i32 m0, s41, 0x4800
	s_add_u32 s52, s50, 0x8000
	s_addc_u32 s53, s51, 0
	global_load_lds_dwordx4 v200, s[52:53]
	s_add_i32 m0, s41, 0x4c00
	s_add_u32 s52, s50, 0xc000
	s_addc_u32 s53, s51, 0
	global_load_lds_dwordx4 v201, s[52:53]
	s_add_u32 s50, s18, 0x80
	s_addc_u32 s51, s19, 0
	s_add_i32 m0, s41, 0x8000
	s_nop 0
	global_load_lds_dwordx4 v200, s[50:51]
	s_add_i32 m0, s41, 0x8400
	s_add_u32 s52, s50, 0x4000
	s_addc_u32 s53, s51, 0
	global_load_lds_dwordx4 v201, s[52:53]
	s_add_i32 m0, s41, 0x8800
	s_add_u32 s52, s50, 0x8000
	s_addc_u32 s53, s51, 0
	global_load_lds_dwordx4 v200, s[52:53]
	s_add_i32 m0, s41, 0x8c00
	s_add_u32 s52, s50, 0xc000
	s_addc_u32 s53, s51, 0
	global_load_lds_dwordx4 v201, s[52:53]
	s_mov_b32 s13, 0
	s_mov_b32 s14, 0
	s_waitcnt vmcnt(8)
	s_barrier
	v_add_u32_e32 v202, 16, v196
	v_add_u32_e32 v203, 16, v197
	ds_read_b128 v[156:159], v202
	ds_read_b128 v[188:191], v203
	ds_read_b128 v[192:195], v202 offset:2048
	ds_read_b128 v[140:143], v198 offset:0
	ds_read_b128 v[144:147], v198 offset:2048
	ds_read_b128 v[148:151], v198 offset:4096
	ds_read_b128 v[152:155], v198 offset:6144
	ds_read_b128 v[208:211], v203 offset:2048
	ds_read_b128 v[216:219], v199 offset:0
	ds_read_b128 v[220:223], v199 offset:2048
	ds_read_b128 v[224:227], v199 offset:4096
	ds_read_b128 v[228:231], v199 offset:6144
	s_setprio 1
.LBB1_56:
	s_mul_i32 s41, s13, 0x4000
	s_add_i32 s41, s41, 16
	s_add_i32 s15, s41, 0x4000
	s_cmp_eq_u32 s13, 2
	s_cselect_b32 s15, 16, s15
	s_add_i32 s41, s41, s54
	s_add_i32 s32, s14, 1
	s_min_u32 s32, s32, 15
	s_lshl_b32 s32, s32, 7
	s_add_u32 s50, s18, s32
	s_addc_u32 s51, s19, 0
	s_add_u32 s46, s28, s32
	s_addc_u32 s47, s29, 0
	s_add_u32 s50, s50, 0x20000
	s_addc_u32 s51, s51, 0
	s_waitcnt lgkmcnt(5)
	v_mfma_f32_16x16x32_bf16 v[124:127], v[140:143], v[156:159], v[124:127]
	v_mfma_f32_16x16x32_bf16 v[120:123], v[144:147], v[156:159], v[120:123]
	v_mfma_f32_16x16x32_bf16 v[116:119], v[148:151], v[156:159], v[116:119]
	v_mfma_f32_16x16x32_bf16 v[112:115], v[152:155], v[156:159], v[112:115]
	ds_read_b128 v[156:159], v202 offset:4096
	s_waitcnt lgkmcnt(1)
	v_mfma_f32_16x16x32_bf16 v[124:127], v[216:219], v[188:191], v[124:127]
	v_mfma_f32_16x16x32_bf16 v[120:123], v[220:223], v[188:191], v[120:123]
	v_mfma_f32_16x16x32_bf16 v[116:119], v[224:227], v[188:191], v[116:119]
	v_mfma_f32_16x16x32_bf16 v[112:115], v[228:231], v[188:191], v[112:115]
	ds_read_b128 v[188:191], v203 offset:4096
	s_waitcnt lgkmcnt(2)
	v_mfma_f32_16x16x32_bf16 v[108:111], v[140:143], v[192:195], v[108:111]
	v_mfma_f32_16x16x32_bf16 v[104:107], v[144:147], v[192:195], v[104:107]
	v_mfma_f32_16x16x32_bf16 v[100:103], v[148:151], v[192:195], v[100:103]
	v_mfma_f32_16x16x32_bf16 v[96:99], v[152:155], v[192:195], v[96:99]
	ds_read_b128 v[192:195], v202 offset:6144
	s_waitcnt lgkmcnt(3)
	v_mfma_f32_16x16x32_bf16 v[108:111], v[216:219], v[208:211], v[108:111]
	v_mfma_f32_16x16x32_bf16 v[104:107], v[220:223], v[208:211], v[104:107]
	v_mfma_f32_16x16x32_bf16 v[100:103], v[224:227], v[208:211], v[100:103]
	v_mfma_f32_16x16x32_bf16 v[96:99], v[228:231], v[208:211], v[96:99]
	ds_read_b128 v[208:211], v203 offset:6144
	v_add_u32_e32 v202, s15, v196
	v_add_u32_e32 v203, s15, v197
	s_waitcnt lgkmcnt(3)
	v_mfma_f32_16x16x32_bf16 v[84:87], v[140:143], v[156:159], v[84:87]
	v_mfma_f32_16x16x32_bf16 v[72:75], v[144:147], v[156:159], v[72:75]
	v_mfma_f32_16x16x32_bf16 v[68:71], v[148:151], v[156:159], v[68:71]
	v_mfma_f32_16x16x32_bf16 v[64:67], v[152:155], v[156:159], v[64:67]
	s_waitcnt vmcnt(4)
	s_waitcnt lgkmcnt(0)
	s_barrier
	s_add_i32 m0, s54, 0xc010
	v_mfma_f32_16x16x32_bf16 v[84:87], v[216:219], v[188:191], v[84:87]
	global_load_lds_dwordx4 v200, s[46:47]
	s_add_i32 m0, s54, 0xc410
	s_add_u32 s52, s46, 0x4000
	s_addc_u32 s53, s47, 0
	v_mfma_f32_16x16x32_bf16 v[72:75], v[220:223], v[188:191], v[72:75]
	global_load_lds_dwordx4 v201, s[52:53]
	s_add_i32 m0, s54, 0xc810
	s_add_u32 s52, s46, 0x8000
	s_addc_u32 s53, s47, 0
	v_mfma_f32_16x16x32_bf16 v[68:71], v[224:227], v[188:191], v[68:71]
	global_load_lds_dwordx4 v200, s[52:53]
	v_mfma_f32_16x16x32_bf16 v[64:67], v[228:231], v[188:191], v[64:67]
	ds_read_b128 v[156:159], v202
	s_add_i32 m0, s54, 0xcc10
	s_add_u32 s52, s46, 0xc000
	s_addc_u32 s53, s47, 0
	v_mfma_f32_16x16x32_bf16 v[60:63], v[140:143], v[192:195], v[60:63]
	global_load_lds_dwordx4 v201, s[52:53]
	s_add_i32 m0, s41, 0x0
	v_mfma_f32_16x16x32_bf16 v[56:59], v[144:147], v[192:195], v[56:59]
	global_load_lds_dwordx4 v200, s[50:51]
	s_add_i32 m0, s41, 0x400
	s_add_u32 s52, s50, 0x4000
	s_addc_u32 s53, s51, 0
	v_mfma_f32_16x16x32_bf16 v[52:55], v[148:151], v[192:195], v[52:55]
	global_load_lds_dwordx4 v201, s[52:53]
	v_mfma_f32_16x16x32_bf16 v[48:51], v[152:155], v[192:195], v[48:51]
	ds_read_b128 v[188:191], v203
	s_add_i32 m0, s41, 0x800
	s_add_u32 s52, s50, 0x8000
	s_addc_u32 s53, s51, 0
	v_mfma_f32_16x16x32_bf16 v[60:63], v[216:219], v[208:211], v[60:63]
	global_load_lds_dwordx4 v200, s[52:53]
	s_add_i32 m0, s41, 0xc00
	s_add_u32 s52, s50, 0xc000
	s_addc_u32 s53, s51, 0
	v_mfma_f32_16x16x32_bf16 v[56:59], v[220:223], v[208:211], v[56:59]
	global_load_lds_dwordx4 v201, s[52:53]
	v_mfma_f32_16x16x32_bf16 v[52:55], v[224:227], v[208:211], v[52:55]
	v_mfma_f32_16x16x32_bf16 v[48:51], v[228:231], v[208:211], v[48:51]
	ds_read_b128 v[192:195], v202 offset:2048
	ds_read_b128 v[208:211], v203 offset:2048
	s_add_i32 s42, s13, 1
	s_cmp_lg_u32 s13, 2
	s_cselect_b32 s13, s42, 0
	s_mul_i32 s41, s13, 0x4000
	s_add_i32 s41, s41, 16
	s_add_i32 s15, s41, 0x4000
	s_cmp_eq_u32 s13, 2
	s_cselect_b32 s15, 16, s15
	s_add_i32 s41, s41, s54
	s_add_i32 s32, s14, 2
	s_min_u32 s32, s32, 15
	s_lshl_b32 s32, s32, 7
	s_add_u32 s50, s18, s32
	s_addc_u32 s51, s19, 0
	s_waitcnt lgkmcnt(3)
	v_mfma_f32_16x16x32_bf16 v[44:47], v[140:143], v[156:159], v[44:47]
	v_mfma_f32_16x16x32_bf16 v[40:43], v[144:147], v[156:159], v[40:43]
	v_mfma_f32_16x16x32_bf16 v[36:39], v[148:151], v[156:159], v[36:39]
	v_mfma_f32_16x16x32_bf16 v[32:35], v[152:155], v[156:159], v[32:35]
	ds_read_b128 v[156:159], v202 offset:4096
	s_waitcnt lgkmcnt(3)
	v_mfma_f32_16x16x32_bf16 v[44:47], v[216:219], v[188:191], v[44:47]
	v_mfma_f32_16x16x32_bf16 v[40:43], v[220:223], v[188:191], v[40:43]
	v_mfma_f32_16x16x32_bf16 v[36:39], v[224:227], v[188:191], v[36:39]
	v_mfma_f32_16x16x32_bf16 v[32:35], v[228:231], v[188:191], v[32:35]
	ds_read_b128 v[188:191], v203 offset:4096
	s_waitcnt lgkmcnt(3)
	v_mfma_f32_16x16x32_bf16 v[28:31], v[140:143], v[192:195], v[28:31]
	v_mfma_f32_16x16x32_bf16 v[24:27], v[144:147], v[192:195], v[24:27]
	v_mfma_f32_16x16x32_bf16 v[20:23], v[148:151], v[192:195], v[20:23]
	v_mfma_f32_16x16x32_bf16 v[16:19], v[152:155], v[192:195], v[16:19]
	ds_read_b128 v[192:195], v202 offset:6144
	s_waitcnt lgkmcnt(3)
	v_mfma_f32_16x16x32_bf16 v[28:31], v[216:219], v[208:211], v[28:31]
	v_mfma_f32_16x16x32_bf16 v[24:27], v[220:223], v[208:211], v[24:27]
	v_mfma_f32_16x16x32_bf16 v[20:23], v[224:227], v[208:211], v[20:23]
	v_mfma_f32_16x16x32_bf16 v[16:19], v[228:231], v[208:211], v[16:19]
	ds_read_b128 v[208:211], v203 offset:6144
	v_add_u32_e32 v202, s15, v196
	v_add_u32_e32 v203, s15, v197
	s_waitcnt lgkmcnt(3)
	v_mfma_f32_16x16x32_bf16 v[12:15], v[140:143], v[156:159], v[12:15]
	v_mfma_f32_16x16x32_bf16 v[8:11], v[144:147], v[156:159], v[8:11]
	v_mfma_f32_16x16x32_bf16 v[4:7], v[148:151], v[156:159], v[4:7]
	v_mfma_f32_16x16x32_bf16 v[0:3], v[152:155], v[156:159], v[0:3]
	s_waitcnt vmcnt(4)
	s_waitcnt lgkmcnt(0)
	s_barrier
	s_add_i32 m0, s41, 0x0
	v_mfma_f32_16x16x32_bf16 v[12:15], v[216:219], v[188:191], v[12:15]
	global_load_lds_dwordx4 v200, s[50:51]
	s_add_i32 m0, s41, 0x400
	s_add_u32 s52, s50, 0x4000
	s_addc_u32 s53, s51, 0
	v_mfma_f32_16x16x32_bf16 v[8:11], v[220:223], v[188:191], v[8:11]
	global_load_lds_dwordx4 v201, s[52:53]
	s_add_i32 m0, s41, 0x800
	s_add_u32 s52, s50, 0x8000
	s_addc_u32 s53, s51, 0
	v_mfma_f32_16x16x32_bf16 v[4:7], v[224:227], v[188:191], v[4:7]
	global_load_lds_dwordx4 v200, s[52:53]
	v_mfma_f32_16x16x32_bf16 v[0:3], v[228:231], v[188:191], v[0:3]
	ds_read_b128 v[156:159], v202
	s_add_i32 m0, s41, 0xc00
	s_add_u32 s52, s50, 0xc000
	s_addc_u32 s53, s51, 0
	v_mfma_f32_16x16x32_bf16 v[76:79], v[140:143], v[192:195], v[76:79]
	global_load_lds_dwordx4 v201, s[52:53]
	v_mfma_f32_16x16x32_bf16 v[80:83], v[144:147], v[192:195], v[80:83]
	v_mfma_f32_16x16x32_bf16 v[88:91], v[148:151], v[192:195], v[88:91]
	v_mfma_f32_16x16x32_bf16 v[92:95], v[152:155], v[192:195], v[92:95]
	ds_read_b128 v[188:191], v203
	v_mfma_f32_16x16x32_bf16 v[76:79], v[216:219], v[208:211], v[76:79]
	v_mfma_f32_16x16x32_bf16 v[80:83], v[220:223], v[208:211], v[80:83]
	v_mfma_f32_16x16x32_bf16 v[88:91], v[224:227], v[208:211], v[88:91]
	v_mfma_f32_16x16x32_bf16 v[92:95], v[228:231], v[208:211], v[92:95]
	ds_read_b128 v[192:195], v202 offset:2048
	ds_read_b128 v[140:143], v198 offset:0
	ds_read_b128 v[144:147], v198 offset:2048
	ds_read_b128 v[148:151], v198 offset:4096
	ds_read_b128 v[152:155], v198 offset:6144
	ds_read_b128 v[208:211], v203 offset:2048
	ds_read_b128 v[216:219], v199 offset:0
	ds_read_b128 v[220:223], v199 offset:2048
	ds_read_b128 v[224:227], v199 offset:4096
	ds_read_b128 v[228:231], v199 offset:6144
	s_add_i32 s42, s13, 1
	s_cmp_lg_u32 s13, 2
	s_cselect_b32 s13, s42, 0
	s_add_i32 s14, s14, 1
	s_cmp_eq_u32 s14, 16
	s_cbranch_scc0 .LBB1_56
	s_waitcnt lgkmcnt(0)
	s_setprio 0
	s_cmpk_lt_i32 s7, 0x80
	v_readlane_b32 s10, v242, 5
	s_waitcnt vmcnt(0)
	s_cselect_b64 s[8:9], -1, 0
	v_readlane_b32 s11, v242, 6
	s_and_b64 s[8:9], s[10:11], s[8:9]
	s_mov_b64 s[42:43], -1
	s_and_b64 vcc, exec, s[8:9]
	v_cvt_pk_bf16_f32 v124, v124, v125
	v_cvt_pk_bf16_f32 v125, v126, v127
	v_cvt_pk_bf16_f32 v120, v120, v121
	v_cvt_pk_bf16_f32 v121, v122, v123
	v_cvt_pk_bf16_f32 v116, v116, v117
	v_cvt_pk_bf16_f32 v117, v118, v119
	v_cvt_pk_bf16_f32 v112, v112, v113
	v_cvt_pk_bf16_f32 v113, v114, v115
	v_cvt_pk_bf16_f32 v108, v108, v109
	v_cvt_pk_bf16_f32 v109, v110, v111
	v_cvt_pk_bf16_f32 v104, v104, v105
	v_cvt_pk_bf16_f32 v105, v106, v107
	v_cvt_pk_bf16_f32 v100, v100, v101
	v_cvt_pk_bf16_f32 v101, v102, v103
	v_cvt_pk_bf16_f32 v96, v96, v97
	v_cvt_pk_bf16_f32 v97, v98, v99
	v_cvt_pk_bf16_f32 v84, v84, v85
	v_cvt_pk_bf16_f32 v85, v86, v87
	v_cvt_pk_bf16_f32 v72, v72, v73
	v_cvt_pk_bf16_f32 v73, v74, v75
	v_cvt_pk_bf16_f32 v68, v68, v69
	v_cvt_pk_bf16_f32 v69, v70, v71
	v_cvt_pk_bf16_f32 v64, v64, v65
	v_cvt_pk_bf16_f32 v65, v66, v67
	v_cvt_pk_bf16_f32 v60, v60, v61
	v_cvt_pk_bf16_f32 v61, v62, v63
	v_cvt_pk_bf16_f32 v56, v56, v57
	v_cvt_pk_bf16_f32 v57, v58, v59
	v_cvt_pk_bf16_f32 v52, v52, v53
	v_cvt_pk_bf16_f32 v53, v54, v55
	v_cvt_pk_bf16_f32 v48, v48, v49
	v_cvt_pk_bf16_f32 v49, v50, v51
	v_cvt_pk_bf16_f32 v44, v44, v45
	v_cvt_pk_bf16_f32 v45, v46, v47
	v_cvt_pk_bf16_f32 v40, v40, v41
	v_cvt_pk_bf16_f32 v41, v42, v43
	v_cvt_pk_bf16_f32 v36, v36, v37
	v_cvt_pk_bf16_f32 v37, v38, v39
	v_cvt_pk_bf16_f32 v32, v32, v33
	v_cvt_pk_bf16_f32 v33, v34, v35
	v_cvt_pk_bf16_f32 v28, v28, v29
	v_cvt_pk_bf16_f32 v29, v30, v31
	v_cvt_pk_bf16_f32 v24, v24, v25
	v_cvt_pk_bf16_f32 v25, v26, v27
	v_cvt_pk_bf16_f32 v20, v20, v21
	v_cvt_pk_bf16_f32 v21, v22, v23
	v_cvt_pk_bf16_f32 v16, v16, v17
	v_cvt_pk_bf16_f32 v17, v18, v19
	v_cvt_pk_bf16_f32 v12, v12, v13
	v_cvt_pk_bf16_f32 v13, v14, v15
	v_cvt_pk_bf16_f32 v14, v8, v9
	v_cvt_pk_bf16_f32 v15, v10, v11
	v_cvt_pk_bf16_f32 v8, v4, v5
	v_cvt_pk_bf16_f32 v9, v6, v7
	v_cvt_pk_bf16_f32 v10, v0, v1
	v_cvt_pk_bf16_f32 v11, v2, v3
	v_cvt_pk_bf16_f32 v2, v76, v77
	v_cvt_pk_bf16_f32 v3, v78, v79
	v_cvt_pk_bf16_f32 v6, v80, v81
	v_cvt_pk_bf16_f32 v7, v82, v83
	v_cvt_pk_bf16_f32 v0, v88, v89
	v_cvt_pk_bf16_f32 v1, v90, v91
	v_cvt_pk_bf16_f32 v4, v92, v93
	v_cvt_pk_bf16_f32 v5, v94, v95
	s_waitcnt vmcnt(0)
	s_barrier
	s_cbranch_vccnz .LBB1_59
	s_load_dwordx16 s[64:79], s[0:1], 0x140
	v_or_b32_e32 v18, s4, v135
	v_add_u32_e32 v18, s6, v18
	v_lshl_or_b32 v19, v136, 2, s40
	v_or_b32_e32 v22, s5, v19
	v_ashrrev_i32_e32 v19, 31, v18
	v_lshlrev_b64 v[26:27], 12, v[18:19]
	v_ashrrev_i32_e32 v23, 31, v22
	s_waitcnt lgkmcnt(0)
	v_lshl_add_u64 v[26:27], s[76:77], 0, v[26:27]
	v_lshlrev_b64 v[22:23], 1, v[22:23]
	v_lshl_add_u64 v[26:27], v[26:27], 0, v[22:23]
	global_store_dwordx2 v[26:27], v[124:125], off
	global_store_dwordx2 v[26:27], v[120:121], off offset:32
	global_store_dwordx2 v[26:27], v[116:117], off offset:64
	global_store_dwordx2 v[26:27], v[112:113], off offset:96
	v_or_b32_e32 v26, 16, v18
	v_ashrrev_i32_e32 v27, 31, v26
	v_lshlrev_b64 v[26:27], 12, v[26:27]
	v_lshl_add_u64 v[26:27], s[76:77], 0, v[26:27]
	v_lshl_add_u64 v[26:27], v[26:27], 0, v[22:23]
	global_store_dwordx2 v[26:27], v[108:109], off
	global_store_dwordx2 v[26:27], v[104:105], off offset:32
	global_store_dwordx2 v[26:27], v[100:101], off offset:64
	global_store_dwordx2 v[26:27], v[96:97], off offset:96
	v_or_b32_e32 v26, 32, v18
	v_ashrrev_i32_e32 v27, 31, v26
	v_lshlrev_b64 v[26:27], 12, v[26:27]
	v_lshl_add_u64 v[26:27], s[76:77], 0, v[26:27]
	v_lshl_add_u64 v[26:27], v[26:27], 0, v[22:23]
	global_store_dwordx2 v[26:27], v[84:85], off
	global_store_dwordx2 v[26:27], v[72:73], off offset:32
	global_store_dwordx2 v[26:27], v[68:69], off offset:64
	global_store_dwordx2 v[26:27], v[64:65], off offset:96
	v_or_b32_e32 v26, 48, v18
	v_ashrrev_i32_e32 v27, 31, v26
	v_lshlrev_b64 v[26:27], 12, v[26:27]
	v_lshl_add_u64 v[26:27], s[76:77], 0, v[26:27]
	v_lshl_add_u64 v[26:27], v[26:27], 0, v[22:23]
	global_store_dwordx2 v[26:27], v[60:61], off
	global_store_dwordx2 v[26:27], v[56:57], off offset:32
	global_store_dwordx2 v[26:27], v[52:53], off offset:64
	global_store_dwordx2 v[26:27], v[48:49], off offset:96
	v_or_b32_e32 v26, 64, v18
	v_ashrrev_i32_e32 v27, 31, v26
	v_lshlrev_b64 v[26:27], 12, v[26:27]
	v_lshl_add_u64 v[26:27], s[76:77], 0, v[26:27]
	v_lshl_add_u64 v[26:27], v[26:27], 0, v[22:23]
	global_store_dwordx2 v[26:27], v[44:45], off
	global_store_dwordx2 v[26:27], v[40:41], off offset:32
	global_store_dwordx2 v[26:27], v[36:37], off offset:64
	global_store_dwordx2 v[26:27], v[32:33], off offset:96
	v_or_b32_e32 v26, 0x50, v18
	v_ashrrev_i32_e32 v27, 31, v26
	v_lshlrev_b64 v[26:27], 12, v[26:27]
	v_lshl_add_u64 v[26:27], s[76:77], 0, v[26:27]
	v_lshl_add_u64 v[26:27], v[26:27], 0, v[22:23]
	global_store_dwordx2 v[26:27], v[28:29], off
	global_store_dwordx2 v[26:27], v[24:25], off offset:32
	global_store_dwordx2 v[26:27], v[20:21], off offset:64
	global_store_dwordx2 v[26:27], v[16:17], off offset:96
	v_or_b32_e32 v26, 0x60, v18
	v_ashrrev_i32_e32 v27, 31, v26
	v_lshlrev_b64 v[26:27], 12, v[26:27]
	v_lshl_add_u64 v[26:27], s[76:77], 0, v[26:27]
	v_or_b32_e32 v18, 0x70, v18
	v_lshl_add_u64 v[26:27], v[26:27], 0, v[22:23]
	v_ashrrev_i32_e32 v19, 31, v18
	global_store_dwordx2 v[26:27], v[12:13], off
	global_store_dwordx2 v[26:27], v[14:15], off offset:32
	global_store_dwordx2 v[26:27], v[8:9], off offset:64
	global_store_dwordx2 v[26:27], v[10:11], off offset:96
	v_lshlrev_b64 v[18:19], 12, v[18:19]
	v_lshl_add_u64 v[18:19], s[76:77], 0, v[18:19]
	s_load_dwordx16 s[64:79], s[0:1], 0x100
	v_lshl_add_u64 v[18:19], v[18:19], 0, v[22:23]
	s_mov_b64 s[42:43], 0
	global_store_dwordx2 v[18:19], v[2:3], off
	global_store_dwordx2 v[18:19], v[6:7], off offset:32
	global_store_dwordx2 v[18:19], v[0:1], off offset:64
	global_store_dwordx2 v[18:19], v[4:5], off offset:96

.LBB1_1179:
	v_mov_b32_e32 v138, v162
	s_lshl_b32 s6, s5, 8
	v_readfirstlane_b32 s7, v138
	v_lshrrev_b32_e32 v0, 3, v138
	v_and_b32_e32 v0, 6, v0
	s_movk_i32 s11, 0x78
	s_and_b32 s9, s7, 0xffffffc0
	s_waitcnt lgkmcnt(0)
	v_bfe_u32 v2, v138, 2, 4
	v_lshrrev_b32_e64 v0, v0, s11
	s_add_i32 s9, s9, s6
	v_xor_b32_e32 v3, v0, v138
	v_or_b32_e32 v0, s9, v2
	v_ashrrev_i32_e32 v1, 31, v0
	v_lshlrev_b64 v[0:1], 11, v[0:1]
	v_lshlrev_b32_e32 v3, 4, v3
	s_lshl_b32 s30, s4, 7
	v_lshl_add_u64 v[0:1], s[74:75], 0, v[0:1]
	v_and_b32_e32 v128, 48, v3
	s_load_dwordx16 s[80:95], s[0:1], 0xc0
	s_ashr_i32 s8, s7, 6
	v_lshl_add_u64 v[130:131], v[0:1], 0, v[128:129]
	v_or_b32_e32 v0, s30, v2
	v_lshl_add_u32 v0, s8, 5, v0
	v_ashrrev_i32_e32 v1, 31, v0
	v_lshlrev_b64 v[0:1], 11, v[0:1]
	s_waitcnt lgkmcnt(0)
	v_lshl_add_u64 v[0:1], s[84:85], 0, v[0:1]
	v_lshl_add_u64 v[132:133], v[0:1], 0, v[128:129]
	v_lshrrev_b32_e32 v0, 1, v138
	v_and_b32_e32 v0, 6, v0
	v_bfe_u32 v140, v138, 4, 2
	s_lshl_b32 s9, s8, 12
	v_lshrrev_b32_e64 v0, v0, s11
	v_and_b32_e32 v139, 15, v138
	s_lshl_b32 s10, s8, 11
	s_and_b32 s8, s7, 0xffffff80
	v_bitop3_b32 v0, v0, v140, 3 bitop3:0x6c
	s_and_b32 s7, s7, 64
	s_add_i32 s11, s9, 16
	v_lshlrev_b32_e32 v134, 4, v0
	v_or_b32_e32 v0, s7, v139
	s_mov_b32 m0, s11
	v_lshlrev_b32_e32 v135, 6, v0
	s_barrier
	v_lshl_add_u64 v[0:1], v[130:131], 0, s[34:35]
	s_add_i32 m0, s11, 0x400
	s_mov_b64 s[12:13], 0x10000
	v_lshl_add_u64 v[0:1], v[130:131], 0, s[12:13]
	s_add_i32 m0, s11, 0x800
	s_mov_b64 s[12:13], 0x18000
	v_lshl_add_u64 v[0:1], v[130:131], 0, s[12:13]
	s_add_i32 m0, s11, 0xc00
	s_sub_i32 s12, s11, s10
	s_add_i32 m0, s12, 0x4000
	v_lshl_add_u64 v[0:1], v[132:133], 0, s[34:35]
	s_add_i32 m0, s12, 0x4400
	s_mov_b64 s[14:15], 0x8040
	v_lshl_add_u64 v[0:1], v[130:131], 0, 64
	s_add_i32 m0, s11, 0x6000
	s_mov_b64 s[16:17], 0x10040
	v_lshl_add_u64 v[0:1], v[130:131], 0, s[14:15]
	s_add_i32 m0, s11, 0x6400
	v_or_b32_e32 v141, s8, v139
	v_lshl_add_u64 v[0:1], v[130:131], 0, s[16:17]
	s_add_i32 m0, s11, 0x6800
	s_mov_b64 s[16:17], 0x18040
	v_lshl_add_u64 v[0:1], v[130:131], 0, s[16:17]
	s_add_i32 m0, s11, 0x6c00
	v_lshlrev_b32_e32 v128, 6, v141
	v_lshl_add_u64 v[0:1], v[132:133], 0, 64
	s_add_i32 m0, s12, 0xa000
	s_mov_b32 s11, 0
	v_lshl_add_u64 v[0:1], v[132:133], 0, s[14:15]
	s_add_i32 m0, s12, 0xa400
	s_mov_b32 s12, 0
	v_mov_b32_e32 v0, 0
	v_mov_b32_e32 v1, v0
	v_mov_b32_e32 v2, v0
	v_mov_b32_e32 v3, v0
	v_mov_b32_e32 v4, v0
	v_mov_b32_e32 v5, v0
	v_mov_b32_e32 v6, v0
	v_mov_b32_e32 v7, v0
	v_mov_b32_e32 v8, v0
	v_mov_b32_e32 v9, v0
	v_mov_b32_e32 v10, v0
	v_mov_b32_e32 v11, v0
	v_mov_b32_e32 v12, v0
	v_mov_b32_e32 v13, v0
	v_mov_b32_e32 v14, v0
	v_mov_b32_e32 v15, v0
	v_mov_b32_e32 v16, v0
	v_mov_b32_e32 v17, v0
	v_mov_b32_e32 v18, v0
	v_mov_b32_e32 v19, v0
	v_mov_b32_e32 v20, v0
	v_mov_b32_e32 v21, v0
	v_mov_b32_e32 v22, v0
	v_mov_b32_e32 v23, v0
	v_mov_b32_e32 v24, v0
	v_mov_b32_e32 v25, v0
	v_mov_b32_e32 v26, v0
	v_mov_b32_e32 v27, v0
	v_mov_b32_e32 v28, v0
	v_mov_b32_e32 v29, v0
	v_mov_b32_e32 v30, v0
	v_mov_b32_e32 v31, v0
	v_mov_b32_e32 v32, v0
	v_mov_b32_e32 v33, v0
	v_mov_b32_e32 v34, v0
	v_mov_b32_e32 v35, v0
	v_mov_b32_e32 v36, v0
	v_mov_b32_e32 v37, v0
	v_mov_b32_e32 v38, v0
	v_mov_b32_e32 v39, v0
	v_mov_b32_e32 v40, v0
	v_mov_b32_e32 v41, v0
	v_mov_b32_e32 v42, v0
	v_mov_b32_e32 v43, v0
	v_mov_b32_e32 v44, v0
	v_mov_b32_e32 v45, v0
	v_mov_b32_e32 v46, v0
	v_mov_b32_e32 v47, v0
	v_mov_b32_e32 v48, v0
	v_mov_b32_e32 v49, v0
	v_mov_b32_e32 v50, v0
	v_mov_b32_e32 v51, v0
	v_mov_b32_e32 v68, v0
	v_mov_b32_e32 v69, v0
	v_mov_b32_e32 v70, v0
	v_mov_b32_e32 v71, v0
	v_mov_b32_e32 v72, v0
	v_mov_b32_e32 v73, v0
	v_mov_b32_e32 v74, v0
	v_mov_b32_e32 v75, v0
	v_mov_b32_e32 v76, v0
	v_mov_b32_e32 v77, v0
	v_mov_b32_e32 v78, v0
	v_mov_b32_e32 v79, v0
	v_mov_b32_e32 v80, v0
	v_mov_b32_e32 v81, v0
	v_mov_b32_e32 v82, v0
	v_mov_b32_e32 v83, v0
	v_mov_b32_e32 v84, v0
	v_mov_b32_e32 v85, v0
	v_mov_b32_e32 v86, v0
	v_mov_b32_e32 v87, v0
	v_mov_b32_e32 v88, v0
	v_mov_b32_e32 v89, v0
	v_mov_b32_e32 v90, v0
	v_mov_b32_e32 v91, v0
	v_mov_b32_e32 v92, v0
	v_mov_b32_e32 v93, v0
	v_mov_b32_e32 v94, v0
	v_mov_b32_e32 v95, v0
	v_mov_b32_e32 v96, v0
	v_mov_b32_e32 v97, v0
	v_mov_b32_e32 v98, v0
	v_mov_b32_e32 v99, v0
	v_mov_b32_e32 v100, v0
	v_mov_b32_e32 v101, v0
	v_mov_b32_e32 v102, v0
	v_mov_b32_e32 v103, v0
	v_mov_b32_e32 v104, v0
	v_mov_b32_e32 v105, v0
	v_mov_b32_e32 v106, v0
	v_mov_b32_e32 v107, v0
	v_mov_b32_e32 v108, v0
	v_mov_b32_e32 v109, v0
	v_mov_b32_e32 v110, v0
	v_mov_b32_e32 v111, v0
	v_mov_b32_e32 v112, v0
	v_mov_b32_e32 v113, v0
	v_mov_b32_e32 v114, v0
	v_mov_b32_e32 v115, v0
	v_mov_b32_e32 v116, v0
	v_mov_b32_e32 v117, v0
	v_mov_b32_e32 v118, v0
	v_mov_b32_e32 v119, v0
	v_mov_b32_e32 v120, v0
	v_mov_b32_e32 v121, v0
	v_mov_b32_e32 v122, v0
	v_mov_b32_e32 v123, v0
	v_mov_b32_e32 v124, v0
	v_mov_b32_e32 v125, v0
	v_mov_b32_e32 v126, v0
	v_mov_b32_e32 v127, v0
	v_mov_b32_e32 v60, v0
	v_mov_b32_e32 v61, v0
	v_mov_b32_e32 v62, v0
	v_mov_b32_e32 v63, v0
	v_mov_b32_e32 v64, v0
	v_mov_b32_e32 v65, v0
	v_mov_b32_e32 v66, v0
	v_mov_b32_e32 v67, v0
	v_mov_b32_e32 v52, v0
	v_mov_b32_e32 v53, v0
	v_mov_b32_e32 v54, v0
	v_mov_b32_e32 v55, v0
	v_mov_b32_e32 v56, v0
	v_mov_b32_e32 v57, v0
	v_mov_b32_e32 v58, v0
	v_mov_b32_e32 v59, v0
	s_mov_b64 s[16:17], 0x10080
	v_and_b32_e32 v204, 15, v168
	v_lshrrev_b32_e32 v205, 4, v168
	v_bfe_u32 v206, v168, 1, 3
	v_xor_b32_e32 v205, v205, v206
	v_lshlrev_b32_e32 v205, 4, v205
	v_readfirstlane_b32 s15, v162
	v_readfirstlane_b32 s18, v130
	v_readfirstlane_b32 s19, v131
	v_readfirstlane_b32 s28, v132
	v_readfirstlane_b32 s29, v133
	s_lshr_b32 s15, s15, 6
	s_lshl_b32 s54, s15, 12
	s_lshr_b32 s41, s15, 1
	s_and_b32 s42, s15, 1
	v_lshl_add_u32 v206, s41, 6, v204
	v_lshl_add_u32 v196, v206, 7, v205
	v_xor_b32_e32 v197, 64, v196
	v_lshl_add_u32 v206, s42, 6, v204
	v_lshl_add_u32 v198, v206, 7, v205
	v_xor_b32_e32 v199, 64, v198
	v_add_u32_e32 v198, 0xc010, v198
	v_add_u32_e32 v199, 0xc010, v199
	v_lshrrev_b32_e32 v206, 3, v168
	v_and_b32_e32 v207, 7, v168
	v_lshrrev_b32_e32 v204, 1, v206
	v_xor_b32_e32 v207, v207, v204
	v_lshlrev_b32_e32 v207, 4, v207
	v_lshl_add_u32 v200, v206, 11, v207
	v_xor_b32_e32 v201, 64, v200
	s_lshl_b32 s42, s42, 16
	s_sub_u32 s18, s18, s42
	s_subb_u32 s19, s19, 0
	s_add_i32 s41, s54, 16
	s_add_i32 m0, s41, 0x0
	s_nop 0
	global_load_lds_dwordx4 v200, s[18:19]
	s_add_i32 m0, s41, 0x400
	s_add_u32 s52, s18, 0x4000
	s_addc_u32 s53, s19, 0
	global_load_lds_dwordx4 v201, s[52:53]
	s_add_i32 m0, s41, 0x800
	s_add_u32 s52, s18, 0x8000
	s_addc_u32 s53, s19, 0
	global_load_lds_dwordx4 v200, s[52:53]
	s_add_i32 m0, s41, 0xc00
	s_add_u32 s52, s18, 0xc000
	s_addc_u32 s53, s19, 0
	global_load_lds_dwordx4 v201, s[52:53]
	s_add_i32 m0, s54, 0xc010
	s_nop 0
	global_load_lds_dwordx4 v200, s[28:29]
	s_add_i32 m0, s54, 0xc410
	s_add_u32 s52, s28, 0x4000
	s_addc_u32 s53, s29, 0
	global_load_lds_dwordx4 v201, s[52:53]
	s_add_i32 m0, s54, 0xc810
	s_add_u32 s52, s28, 0x8000
	s_addc_u32 s53, s29, 0
	global_load_lds_dwordx4 v200, s[52:53]
	s_add_i32 m0, s54, 0xcc10
	s_add_u32 s52, s28, 0xc000
	s_addc_u32 s53, s29, 0
	global_load_lds_dwordx4 v201, s[52:53]
	s_add_u32 s50, s18, 0x20000
	s_addc_u32 s51, s19, 0
	s_add_i32 m0, s41, 0x4000
	s_nop 0
	global_load_lds_dwordx4 v200, s[50:51]
	s_add_i32 m0, s41, 0x4400
	s_add_u32 s52, s50, 0x4000
	s_addc_u32 s53, s51, 0
	global_load_lds_dwordx4 v201, s[52:53]
	s_add_i32 m0, s41, 0x4800
	s_add_u32 s52, s50, 0x8000
	s_addc_u32 s53, s51, 0
	global_load_lds_dwordx4 v200, s[52:53]
	s_add_i32 m0, s41, 0x4c00
	s_add_u32 s52, s50, 0xc000
	s_addc_u32 s53, s51, 0
	global_load_lds_dwordx4 v201, s[52:53]
	s_add_u32 s50, s18, 0x80
	s_addc_u32 s51, s19, 0
	s_add_i32 m0, s41, 0x8000
	s_nop 0
	global_load_lds_dwordx4 v200, s[50:51]
	s_add_i32 m0, s41, 0x8400
	s_add_u32 s52, s50, 0x4000
	s_addc_u32 s53, s51, 0
	global_load_lds_dwordx4 v201, s[52:53]
	s_add_i32 m0, s41, 0x8800
	s_add_u32 s52, s50, 0x8000
	s_addc_u32 s53, s51, 0
	global_load_lds_dwordx4 v200, s[52:53]
	s_add_i32 m0, s41, 0x8c00
	s_add_u32 s52, s50, 0xc000
	s_addc_u32 s53, s51, 0
	global_load_lds_dwordx4 v201, s[52:53]
	s_mov_b32 s13, 0
	s_mov_b32 s14, 0
	s_waitcnt vmcnt(8)
	s_barrier
	v_add_u32_e32 v202, 16, v196
	v_add_u32_e32 v203, 16, v197
	ds_read_b128 v[158:161], v202
	ds_read_b128 v[188:191], v203
	ds_read_b128 v[192:195], v202 offset:2048
	ds_read_b128 v[142:145], v198 offset:0
	ds_read_b128 v[146:149], v198 offset:2048
	ds_read_b128 v[150:153], v198 offset:4096
	ds_read_b128 v[154:157], v198 offset:6144
	ds_read_b128 v[208:211], v203 offset:2048
	ds_read_b128 v[216:219], v199 offset:0
	ds_read_b128 v[220:223], v199 offset:2048
	ds_read_b128 v[224:227], v199 offset:4096
	ds_read_b128 v[228:231], v199 offset:6144
	s_setprio 1
.LBB1_1180:
	s_mul_i32 s41, s13, 0x4000
	s_add_i32 s41, s41, 16
	s_add_i32 s15, s41, 0x4000
	s_cmp_eq_u32 s13, 2
	s_cselect_b32 s15, 16, s15
	s_add_i32 s41, s41, s54
	s_add_i32 s32, s14, 1
	s_min_u32 s32, s32, 15
	s_lshl_b32 s32, s32, 7
	s_add_u32 s50, s18, s32
	s_addc_u32 s51, s19, 0
	s_add_u32 s46, s28, s32
	s_addc_u32 s47, s29, 0
	s_add_u32 s50, s50, 0x20000
	s_addc_u32 s51, s51, 0
	s_waitcnt lgkmcnt(5)
	v_mfma_f32_16x16x32_bf16 v[124:127], v[142:145], v[158:161], v[124:127]
	v_mfma_f32_16x16x32_bf16 v[120:123], v[146:149], v[158:161], v[120:123]
	v_mfma_f32_16x16x32_bf16 v[116:119], v[150:153], v[158:161], v[116:119]
	v_mfma_f32_16x16x32_bf16 v[112:115], v[154:157], v[158:161], v[112:115]
	ds_read_b128 v[158:161], v202 offset:4096
	s_waitcnt lgkmcnt(1)
	v_mfma_f32_16x16x32_bf16 v[124:127], v[216:219], v[188:191], v[124:127]
	v_mfma_f32_16x16x32_bf16 v[120:123], v[220:223], v[188:191], v[120:123]
	v_mfma_f32_16x16x32_bf16 v[116:119], v[224:227], v[188:191], v[116:119]
	v_mfma_f32_16x16x32_bf16 v[112:115], v[228:231], v[188:191], v[112:115]
	ds_read_b128 v[188:191], v203 offset:4096
	s_waitcnt lgkmcnt(2)
	v_mfma_f32_16x16x32_bf16 v[108:111], v[142:145], v[192:195], v[108:111]
	v_mfma_f32_16x16x32_bf16 v[104:107], v[146:149], v[192:195], v[104:107]
	v_mfma_f32_16x16x32_bf16 v[100:103], v[150:153], v[192:195], v[100:103]
	v_mfma_f32_16x16x32_bf16 v[96:99], v[154:157], v[192:195], v[96:99]
	ds_read_b128 v[192:195], v202 offset:6144
	s_waitcnt lgkmcnt(3)
	v_mfma_f32_16x16x32_bf16 v[108:111], v[216:219], v[208:211], v[108:111]
	v_mfma_f32_16x16x32_bf16 v[104:107], v[220:223], v[208:211], v[104:107]
	v_mfma_f32_16x16x32_bf16 v[100:103], v[224:227], v[208:211], v[100:103]
	v_mfma_f32_16x16x32_bf16 v[96:99], v[228:231], v[208:211], v[96:99]
	ds_read_b128 v[208:211], v203 offset:6144
	v_add_u32_e32 v202, s15, v196
	v_add_u32_e32 v203, s15, v197
	s_waitcnt lgkmcnt(3)
	v_mfma_f32_16x16x32_bf16 v[92:95], v[142:145], v[158:161], v[92:95]
	v_mfma_f32_16x16x32_bf16 v[88:91], v[146:149], v[158:161], v[88:91]
	v_mfma_f32_16x16x32_bf16 v[84:87], v[150:153], v[158:161], v[84:87]
	v_mfma_f32_16x16x32_bf16 v[80:83], v[154:157], v[158:161], v[80:83]
	s_waitcnt vmcnt(4)
	s_waitcnt lgkmcnt(0)
	s_barrier
	s_add_i32 m0, s54, 0xc010
	v_mfma_f32_16x16x32_bf16 v[92:95], v[216:219], v[188:191], v[92:95]
	global_load_lds_dwordx4 v200, s[46:47]
	s_add_i32 m0, s54, 0xc410
	s_add_u32 s52, s46, 0x4000
	s_addc_u32 s53, s47, 0
	v_mfma_f32_16x16x32_bf16 v[88:91], v[220:223], v[188:191], v[88:91]
	global_load_lds_dwordx4 v201, s[52:53]
	s_add_i32 m0, s54, 0xc810
	s_add_u32 s52, s46, 0x8000
	s_addc_u32 s53, s47, 0
	v_mfma_f32_16x16x32_bf16 v[84:87], v[224:227], v[188:191], v[84:87]
	global_load_lds_dwordx4 v200, s[52:53]
	v_mfma_f32_16x16x32_bf16 v[80:83], v[228:231], v[188:191], v[80:83]
	ds_read_b128 v[158:161], v202
	s_add_i32 m0, s54, 0xcc10
	s_add_u32 s52, s46, 0xc000
	s_addc_u32 s53, s47, 0
	v_mfma_f32_16x16x32_bf16 v[76:79], v[142:145], v[192:195], v[76:79]
	global_load_lds_dwordx4 v201, s[52:53]
	s_add_i32 m0, s41, 0x0
	v_mfma_f32_16x16x32_bf16 v[72:75], v[146:149], v[192:195], v[72:75]
	global_load_lds_dwordx4 v200, s[50:51]
	s_add_i32 m0, s41, 0x400
	s_add_u32 s52, s50, 0x4000
	s_addc_u32 s53, s51, 0
	v_mfma_f32_16x16x32_bf16 v[68:71], v[150:153], v[192:195], v[68:71]
	global_load_lds_dwordx4 v201, s[52:53]
	v_mfma_f32_16x16x32_bf16 v[48:51], v[154:157], v[192:195], v[48:51]
	ds_read_b128 v[188:191], v203
	s_add_i32 m0, s41, 0x800
	s_add_u32 s52, s50, 0x8000
	s_addc_u32 s53, s51, 0
	v_mfma_f32_16x16x32_bf16 v[76:79], v[216:219], v[208:211], v[76:79]
	global_load_lds_dwordx4 v200, s[52:53]
	s_add_i32 m0, s41, 0xc00
	s_add_u32 s52, s50, 0xc000
	s_addc_u32 s53, s51, 0
	v_mfma_f32_16x16x32_bf16 v[72:75], v[220:223], v[208:211], v[72:75]
	global_load_lds_dwordx4 v201, s[52:53]
	v_mfma_f32_16x16x32_bf16 v[68:71], v[224:227], v[208:211], v[68:71]
	v_mfma_f32_16x16x32_bf16 v[48:51], v[228:231], v[208:211], v[48:51]
	ds_read_b128 v[192:195], v202 offset:2048
	ds_read_b128 v[208:211], v203 offset:2048
	s_add_i32 s42, s13, 1
	s_cmp_lg_u32 s13, 2
	s_cselect_b32 s13, s42, 0
	s_mul_i32 s41, s13, 0x4000
	s_add_i32 s41, s41, 16
	s_add_i32 s15, s41, 0x4000
	s_cmp_eq_u32 s13, 2
	s_cselect_b32 s15, 16, s15
	s_add_i32 s41, s41, s54
	s_add_i32 s32, s14, 2
	s_min_u32 s32, s32, 15
	s_lshl_b32 s32, s32, 7
	s_add_u32 s50, s18, s32
	s_addc_u32 s51, s19, 0
	s_waitcnt lgkmcnt(3)
	v_mfma_f32_16x16x32_bf16 v[44:47], v[142:145], v[158:161], v[44:47]
	v_mfma_f32_16x16x32_bf16 v[40:43], v[146:149], v[158:161], v[40:43]
	v_mfma_f32_16x16x32_bf16 v[36:39], v[150:153], v[158:161], v[36:39]
	v_mfma_f32_16x16x32_bf16 v[32:35], v[154:157], v[158:161], v[32:35]
	ds_read_b128 v[158:161], v202 offset:4096
	s_waitcnt lgkmcnt(3)
	v_mfma_f32_16x16x32_bf16 v[44:47], v[216:219], v[188:191], v[44:47]
	v_mfma_f32_16x16x32_bf16 v[40:43], v[220:223], v[188:191], v[40:43]
	v_mfma_f32_16x16x32_bf16 v[36:39], v[224:227], v[188:191], v[36:39]
	v_mfma_f32_16x16x32_bf16 v[32:35], v[228:231], v[188:191], v[32:35]
	ds_read_b128 v[188:191], v203 offset:4096
	s_waitcnt lgkmcnt(3)
	v_mfma_f32_16x16x32_bf16 v[28:31], v[142:145], v[192:195], v[28:31]
	v_mfma_f32_16x16x32_bf16 v[24:27], v[146:149], v[192:195], v[24:27]
	v_mfma_f32_16x16x32_bf16 v[20:23], v[150:153], v[192:195], v[20:23]
	v_mfma_f32_16x16x32_bf16 v[16:19], v[154:157], v[192:195], v[16:19]
	ds_read_b128 v[192:195], v202 offset:6144
	s_waitcnt lgkmcnt(3)
	v_mfma_f32_16x16x32_bf16 v[28:31], v[216:219], v[208:211], v[28:31]
	v_mfma_f32_16x16x32_bf16 v[24:27], v[220:223], v[208:211], v[24:27]
	v_mfma_f32_16x16x32_bf16 v[20:23], v[224:227], v[208:211], v[20:23]
	v_mfma_f32_16x16x32_bf16 v[16:19], v[228:231], v[208:211], v[16:19]
	ds_read_b128 v[208:211], v203 offset:6144
	v_add_u32_e32 v202, s15, v196
	v_add_u32_e32 v203, s15, v197
	s_waitcnt lgkmcnt(3)
	v_mfma_f32_16x16x32_bf16 v[12:15], v[142:145], v[158:161], v[12:15]
	v_mfma_f32_16x16x32_bf16 v[8:11], v[146:149], v[158:161], v[8:11]
	v_mfma_f32_16x16x32_bf16 v[4:7], v[150:153], v[158:161], v[4:7]
	v_mfma_f32_16x16x32_bf16 v[0:3], v[154:157], v[158:161], v[0:3]
	s_waitcnt vmcnt(4)
	s_waitcnt lgkmcnt(0)
	s_barrier
	s_add_i32 m0, s41, 0x0
	v_mfma_f32_16x16x32_bf16 v[12:15], v[216:219], v[188:191], v[12:15]
	global_load_lds_dwordx4 v200, s[50:51]
	s_add_i32 m0, s41, 0x400
	s_add_u32 s52, s50, 0x4000
	s_addc_u32 s53, s51, 0
	v_mfma_f32_16x16x32_bf16 v[8:11], v[220:223], v[188:191], v[8:11]
	global_load_lds_dwordx4 v201, s[52:53]
	s_add_i32 m0, s41, 0x800
	s_add_u32 s52, s50, 0x8000
	s_addc_u32 s53, s51, 0
	v_mfma_f32_16x16x32_bf16 v[4:7], v[224:227], v[188:191], v[4:7]
	global_load_lds_dwordx4 v200, s[52:53]
	v_mfma_f32_16x16x32_bf16 v[0:3], v[228:231], v[188:191], v[0:3]
	ds_read_b128 v[158:161], v202
	s_add_i32 m0, s41, 0xc00
	s_add_u32 s52, s50, 0xc000
	s_addc_u32 s53, s51, 0
	v_mfma_f32_16x16x32_bf16 v[60:63], v[142:145], v[192:195], v[60:63]
	global_load_lds_dwordx4 v201, s[52:53]
	v_mfma_f32_16x16x32_bf16 v[64:67], v[146:149], v[192:195], v[64:67]
	v_mfma_f32_16x16x32_bf16 v[52:55], v[150:153], v[192:195], v[52:55]
	v_mfma_f32_16x16x32_bf16 v[56:59], v[154:157], v[192:195], v[56:59]
	ds_read_b128 v[188:191], v203
	v_mfma_f32_16x16x32_bf16 v[60:63], v[216:219], v[208:211], v[60:63]
	v_mfma_f32_16x16x32_bf16 v[64:67], v[220:223], v[208:211], v[64:67]
	v_mfma_f32_16x16x32_bf16 v[52:55], v[224:227], v[208:211], v[52:55]
	v_mfma_f32_16x16x32_bf16 v[56:59], v[228:231], v[208:211], v[56:59]
	ds_read_b128 v[192:195], v202 offset:2048
	ds_read_b128 v[142:145], v198 offset:0
	ds_read_b128 v[146:149], v198 offset:2048
	ds_read_b128 v[150:153], v198 offset:4096
	ds_read_b128 v[154:157], v198 offset:6144
	ds_read_b128 v[208:211], v203 offset:2048
	ds_read_b128 v[216:219], v199 offset:0
	ds_read_b128 v[220:223], v199 offset:2048
	ds_read_b128 v[224:227], v199 offset:4096
	ds_read_b128 v[228:231], v199 offset:6144
	s_add_i32 s42, s13, 1
	s_cmp_lg_u32 s13, 2
	s_cselect_b32 s13, s42, 0
	s_add_i32 s14, s14, 1
	s_cmp_eq_u32 s14, 16
	s_cbranch_scc0 .LBB1_1180
	s_waitcnt lgkmcnt(0)
	s_setprio 0
	s_waitcnt vmcnt(0)
	s_waitcnt vmcnt(0)
	s_barrier
	s_load_dwordx8 s[80:87], s[0:1], 0x180
	s_cmp_lt_i32 s4, 64
	v_readlane_b32 s12, v242, 9
	s_cselect_b64 s[10:11], -1, 0
	v_readlane_b32 s13, v242, 10
	s_and_b64 s[10:11], s[12:13], s[10:11]
	s_mov_b64 s[38:39], -1
	s_and_b64 vcc, exec, s[10:11]
	s_movk_i32 s12, 0x2020
	s_cbranch_vccnz .LBB1_1291
	v_or_b32_e32 v128, s6, v139
	v_add_u32_e32 v132, s8, v128
	v_lshl_or_b32 v128, v140, 2, s30
	v_or_b32_e32 v130, s7, v128
	v_lshlrev_b32_e32 v134, 5, v132
	s_movk_i32 s8, 0x1fff
	v_ashrrev_i32_e32 v135, 31, v134
	v_cmp_lt_i32_e32 vcc, s8, v130
	s_and_saveexec_b64 s[8:9], vcc
	s_xor_b64 s[40:41], exec, s[8:9]
	s_cbranch_execz .LBB1_1186
	v_cmp_gt_u32_e64 s[38:39], s12, v130
	s_and_saveexec_b64 s[42:43], s[38:39]
	s_cbranch_execz .LBB1_1185
	v_add_u32_e32 v128, 0xffffe000, v130
	v_lshl_add_u64 v[136:137], v[134:135], 2, s[78:79]
	v_lshlrev_b64 v[142:143], 2, v[128:129]
	v_lshl_add_u64 v[136:137], v[136:137], 0, v[142:143]
	v_lshl_add_u64 v[142:143], s[22:23], 0, v[142:143]
	global_load_dwordx4 v[142:145], v[142:143], off
	s_waitcnt vmcnt(0)
	v_pk_add_f32 v[144:145], v[126:127], v[144:145]
	v_pk_add_f32 v[142:143], v[124:125], v[142:143]
	global_store_dwordx4 v[136:137], v[142:145], off
